# gMLP tile hand-off among the 64 gMLP workgroups without the L2 writeback (its G-tile stores are write-through) and without the second invalidate
# speedup vs baseline: 1.0085x; 1.0021x over previous
.LBB0_1001:
	s_mov_b64 s[56:57], s[16:17]
	s_waitcnt vmcnt(0)
	v_cmp_eq_u32_e32 vcc, 0, v166
	s_waitcnt vmcnt(0) lgkmcnt(0)
	s_barrier
	s_and_saveexec_b64 s[4:5], vcc
	s_cbranch_execz .LBB0_1013
	s_load_dwordx2 s[6:7], s[56:57], 0x98
	v_readlane_b32 s10, v255, 21
	s_mov_b64 s[8:9], exec
	v_readlane_b32 s11, v255, 22
	s_waitcnt lgkmcnt(0)
	s_add_u32 s6, s6, s10
	s_waitcnt vmcnt(0)
	v_mbcnt_lo_u32_b32 v0, s8, 0
	s_addc_u32 s7, s7, s11
	s_add_u32 s6, s6, 0x2000
	v_mbcnt_hi_u32_b32 v0, s9, v0
	s_addc_u32 s7, s7, 0
	v_cmp_eq_u32_e32 vcc, 0, v0
	s_and_saveexec_b64 s[10:11], vcc
	s_cbranch_execz .LBB0_1004
	s_bcnt1_i32_b64 s8, s[8:9]
	v_mov_b32_e32 v0, s8
	global_atomic_add v145, v0, s[6:7]

.LBB0_1012:
	s_waitcnt vmcnt(0)
	v_readlane_b32 s6, v255, 5
	s_nop 1
	v_mov_b32_e32 v0, s6
	ds_write_b32 v0, v145
